# scan compute body: per-step LDS waits merged pairwise (34 -> 17 waits per chunk, 721 -> 712 instructions)
# baseline (speedup 1.0000x reference)
; #define LAS __attribute__((address_space(3)))
; #define RW_LD(X, s) do { X.d = *(const LAS f32x4*)(bs + (s) * 256); X.k = *(const LAS f32x4*)(bs + 8192 + (s) * 256); X.a = *(const LAS f32x4*)(bs + 16384 + (s) * 256); \
;                          X.p = *(const LAS f32x4*)(bs + 24576 + (s) * 256); X.r = *(const LAS f32x4*)(bs + 32768 + (s) * 256); X.v = *(const LAS float*)(bv + (s) * 64); } while (0)
; #define RW_STEP(X, s) do { float sa = fmaf(S[3], X.k[3], fmaf(S[2], X.k[2], fmaf(S[1], X.k[1], S[0] * X.k[0]))); const f32x4 T = S * X.d + X.v * X.p; sa = -red16(sa); \
;                            S = T + sa * X.a; float y = fmaf(S[3], X.r[3], fmaf(S[2], X.r[2], fmaf(S[1], X.r[1], S[0] * X.r[0]))); y = red16(y); \
;                            yk = fmaf(selv[(s) & 15], y, yk); } while (0)
; #define RW_YST(s) do { if ((s) == 15) { ob[(size_t)(rowbase + c * 32 + seg) * D + 512 + h * 64 + vrow] = f2bf(yk); yk = 0.f; } } while (0)
; __device__ __forceinline__ void rwkv_scan(const Params& p, LAS unsigned char* lds, int rowbase, int T, int h, int q4, const float* S0, float* Sout) {
;     ...
;         if (comp) {
;             const LAS unsigned char* bs = b + seg * 16; const LAS unsigned char* bv = b + 40960 + vloc * 4;
;     ...
;             RwStep xa, xb, xc; float yk = 0.f;
;     ...
;             RW_LD(xa, 0); RW_LD(xb, 1);
; #pragma unroll
;             for (int s = 0; s < 30; s += 3) {
;                 RW_LD(xc, s + 2); RW_STEP(xa, s); RW_YST(s);
;                 RW_LD(xa, s + 3); RW_STEP(xb, s + 1); RW_YST(s + 1);
;                 RW_LD(xb, s + 4); RW_STEP(xc, s + 2); RW_YST(s + 2);
;             }
.Lrw3_cloop:
	s_barrier
	ds_read_b128 v[76:79], v2 offset:0
	ds_read_b128 v[84:87], v2 offset:16384
	ds_read_b128 v[80:83], v2 offset:8192
	ds_read_b128 v[124:127], v2 offset:24576
	ds_read_b128 v[24:27], v3 offset:0
	ds_read_b128 v[88:91], v2 offset:256
	ds_read_b128 v[96:99], v2 offset:16640
	ds_read_b128 v[92:95], v2 offset:8448
	ds_read_b128 v[128:131], v2 offset:24832
	ds_read_b128 v[100:103], v2 offset:512
	ds_read_b128 v[108:111], v2 offset:16896
	ds_read_b128 v[104:107], v2 offset:8704
	ds_read_b128 v[132:135], v2 offset:25088
	s_waitcnt lgkmcnt(5)
	v_pk_mul_f32 v[72:73], v[12:13], v[76:77]
	v_pk_fma_f32 v[72:73], v[14:15], v[78:79], v[72:73]
	ds_read_b128 v[112:115], v2 offset:768
	v_add_f32_e32 v74, v72, v73
	ds_read_b128 v[120:123], v2 offset:17152
	ds_read_b128 v[116:119], v2 offset:8960
	v_add_f32_dpp v74, v74, v74 quad_perm:[1,0,3,2] row_mask:0xf bank_mask:0xf bound_ctrl:1
	ds_read_b128 v[136:139], v2 offset:25344
	v_pk_fma_f32 v[16:17], v[24:25], v[84:85], v[12:13] op_sel_hi:[0,1,1]
	v_add_f32_dpp v74, v74, v74 quad_perm:[2,3,0,1] row_mask:0xf bank_mask:0xf bound_ctrl:1
	v_pk_fma_f32 v[18:19], v[24:25], v[86:87], v[14:15] op_sel_hi:[0,1,1]
	s_nop 0
	v_add_f32_dpp v74, v74, v74 row_half_mirror row_mask:0xf bank_mask:0xf bound_ctrl:1
	s_nop 1
	v_add_f32_dpp v74, v74, v74 row_mirror row_mask:0xf bank_mask:0xf bound_ctrl:1
	v_pk_fma_f32 v[12:13], v[80:81], v[74:75], v[16:17] op_sel_hi:[1,0,1] neg_lo:[0,1,0] neg_hi:[0,1,0]
	v_pk_fma_f32 v[14:15], v[82:83], v[74:75], v[18:19] op_sel_hi:[1,0,1] neg_lo:[0,1,0] neg_hi:[0,1,0]
	v_pk_mul_f32 v[72:73], v[12:13], v[88:89]
	v_pk_fma_f32 v[72:73], v[14:15], v[90:91], v[72:73]
	ds_read_b128 v[76:79], v2 offset:1024
	v_add_f32_e32 v74, v72, v73
	ds_read_b128 v[84:87], v2 offset:17408
	ds_read_b128 v[80:83], v2 offset:9216
	v_add_f32_dpp v74, v74, v74 quad_perm:[1,0,3,2] row_mask:0xf bank_mask:0xf bound_ctrl:1
	ds_read_b128 v[140:143], v2 offset:25600
	ds_read_b128 v[28:31], v3 offset:16
	v_add_f32_dpp v74, v74, v74 quad_perm:[2,3,0,1] row_mask:0xf bank_mask:0xf bound_ctrl:1
	v_pk_fma_f32 v[16:17], v[24:25], v[96:97], v[12:13] op_sel:[1,0,0] op_sel_hi:[1,1,1]
	v_pk_fma_f32 v[18:19], v[24:25], v[98:99], v[14:15] op_sel:[1,0,0] op_sel_hi:[1,1,1]
	v_add_f32_dpp v74, v74, v74 row_half_mirror row_mask:0xf bank_mask:0xf bound_ctrl:1
	v_pk_mul_f32 v[198:199], v[12:13], v[124:125]
	v_pk_fma_f32 v[198:199], v[14:15], v[126:127], v[198:199]
	v_add_f32_dpp v74, v74, v74 row_mirror row_mask:0xf bank_mask:0xf bound_ctrl:1
	v_add_f32_e32 v144, v198, v199
	v_pk_fma_f32 v[12:13], v[92:93], v[74:75], v[16:17] op_sel_hi:[1,0,1] neg_lo:[0,1,0] neg_hi:[0,1,0]
	v_pk_fma_f32 v[14:15], v[94:95], v[74:75], v[18:19] op_sel_hi:[1,0,1] neg_lo:[0,1,0] neg_hi:[0,1,0]
	s_waitcnt lgkmcnt(6)
	v_pk_mul_f32 v[72:73], v[12:13], v[100:101]
	v_pk_fma_f32 v[72:73], v[14:15], v[102:103], v[72:73]
	ds_read_b128 v[88:91], v2 offset:1280
	v_add_f32_e32 v74, v72, v73
	ds_read_b128 v[96:99], v2 offset:17664
	ds_read_b128 v[92:95], v2 offset:9472
	v_add_f32_dpp v74, v74, v74 quad_perm:[1,0,3,2] row_mask:0xf bank_mask:0xf bound_ctrl:1
	ds_read_b128 v[124:127], v2 offset:25856
	v_pk_fma_f32 v[16:17], v[26:27], v[108:109], v[12:13] op_sel_hi:[0,1,1]
	v_add_f32_dpp v74, v74, v74 quad_perm:[2,3,0,1] row_mask:0xf bank_mask:0xf bound_ctrl:1
	v_pk_fma_f32 v[18:19], v[26:27], v[110:111], v[14:15] op_sel_hi:[0,1,1]
	v_pk_mul_f32 v[198:199], v[12:13], v[128:129]
	v_add_f32_dpp v74, v74, v74 row_half_mirror row_mask:0xf bank_mask:0xf bound_ctrl:1
	v_pk_fma_f32 v[198:199], v[14:15], v[130:131], v[198:199]
	v_add_f32_e32 v145, v198, v199
	v_add_f32_dpp v74, v74, v74 row_mirror row_mask:0xf bank_mask:0xf bound_ctrl:1
	v_pk_fma_f32 v[12:13], v[104:105], v[74:75], v[16:17] op_sel_hi:[1,0,1] neg_lo:[0,1,0] neg_hi:[0,1,0]
	v_pk_fma_f32 v[14:15], v[106:107], v[74:75], v[18:19] op_sel_hi:[1,0,1] neg_lo:[0,1,0] neg_hi:[0,1,0]
	v_pk_mul_f32 v[72:73], v[12:13], v[112:113]
	v_pk_fma_f32 v[72:73], v[14:15], v[114:115], v[72:73]
	ds_read_b128 v[100:103], v2 offset:1536
	v_add_f32_e32 v74, v72, v73
	ds_read_b128 v[108:111], v2 offset:17920
	ds_read_b128 v[104:107], v2 offset:9728
	v_add_f32_dpp v74, v74, v74 quad_perm:[1,0,3,2] row_mask:0xf bank_mask:0xf bound_ctrl:1
	ds_read_b128 v[128:131], v2 offset:26112
	v_pk_fma_f32 v[16:17], v[26:27], v[120:121], v[12:13] op_sel:[1,0,0] op_sel_hi:[1,1,1]
	v_add_f32_dpp v74, v74, v74 quad_perm:[2,3,0,1] row_mask:0xf bank_mask:0xf bound_ctrl:1
	v_pk_fma_f32 v[18:19], v[26:27], v[122:123], v[14:15] op_sel:[1,0,0] op_sel_hi:[1,1,1]
	v_pk_mul_f32 v[198:199], v[12:13], v[132:133]
	v_add_f32_dpp v74, v74, v74 row_half_mirror row_mask:0xf bank_mask:0xf bound_ctrl:1
	v_pk_fma_f32 v[198:199], v[14:15], v[134:135], v[198:199]
	v_add_f32_e32 v146, v198, v199
	v_add_f32_dpp v74, v74, v74 row_mirror row_mask:0xf bank_mask:0xf bound_ctrl:1
	v_pk_fma_f32 v[12:13], v[116:117], v[74:75], v[16:17] op_sel_hi:[1,0,1] neg_lo:[0,1,0] neg_hi:[0,1,0]
	v_pk_fma_f32 v[14:15], v[118:119], v[74:75], v[18:19] op_sel_hi:[1,0,1] neg_lo:[0,1,0] neg_hi:[0,1,0]
	s_waitcnt lgkmcnt(5)
; #define LAS __attribute__((address_space(3)))
; #define RW_LD(X, s) do { X.d = *(const LAS f32x4*)(bs + (s) * 256); X.k = *(const LAS f32x4*)(bs + 8192 + (s) * 256); X.a = *(const LAS f32x4*)(bs + 16384 + (s) * 256); \
;                          X.p = *(const LAS f32x4*)(bs + 24576 + (s) * 256); X.r = *(const LAS f32x4*)(bs + 32768 + (s) * 256); X.v = *(const LAS float*)(bv + (s) * 64); } while (0)
; #define RW_STEP(X, s) do { float sa = fmaf(S[3], X.k[3], fmaf(S[2], X.k[2], fmaf(S[1], X.k[1], S[0] * X.k[0]))); const f32x4 T = S * X.d + X.v * X.p; sa = -red16(sa); \
;                            S = T + sa * X.a; float y = fmaf(S[3], X.r[3], fmaf(S[2], X.r[2], fmaf(S[1], X.r[1], S[0] * X.r[0]))); y = red16(y); \
;                            yk = fmaf(selv[(s) & 15], y, yk); } while (0)
; #define RW_YST(s) do { if ((s) == 15) { ob[(size_t)(rowbase + c * 32 + seg) * D + 512 + h * 64 + vrow] = f2bf(yk); yk = 0.f; } } while (0)
; __device__ __forceinline__ void rwkv_scan(const Params& p, LAS unsigned char* lds, int rowbase, int T, int h, int q4, const float* S0, float* Sout) {
;     ...
;         if (comp) {
;             const LAS unsigned char* bs = b + seg * 16; const LAS unsigned char* bv = b + 40960 + vloc * 4;
;     ...
;             RwStep xa, xb, xc; float yk = 0.f;
;     ...
;             RW_LD(xa, 0); RW_LD(xb, 1);
; #pragma unroll
;             for (int s = 0; s < 30; s += 3) {
;                 RW_LD(xc, s + 2); RW_STEP(xa, s); RW_YST(s);
;                 RW_LD(xa, s + 3); RW_STEP(xb, s + 1); RW_YST(s + 1);
;                 RW_LD(xb, s + 4); RW_STEP(xc, s + 2); RW_YST(s + 2);
;             }
	v_pk_mul_f32 v[72:73], v[12:13], v[76:77]
	v_pk_fma_f32 v[72:73], v[14:15], v[78:79], v[72:73]
	ds_read_b128 v[112:115], v2 offset:1792
	v_add_f32_e32 v74, v72, v73
	ds_read_b128 v[120:123], v2 offset:18176
	ds_read_b128 v[116:119], v2 offset:9984
	v_add_f32_dpp v74, v74, v74 quad_perm:[1,0,3,2] row_mask:0xf bank_mask:0xf bound_ctrl:1
	ds_read_b128 v[132:135], v2 offset:26368
	v_pk_fma_f32 v[16:17], v[28:29], v[84:85], v[12:13] op_sel_hi:[0,1,1]
	v_add_f32_dpp v74, v74, v74 quad_perm:[2,3,0,1] row_mask:0xf bank_mask:0xf bound_ctrl:1
	v_pk_fma_f32 v[18:19], v[28:29], v[86:87], v[14:15] op_sel_hi:[0,1,1]
	v_pk_mul_f32 v[198:199], v[12:13], v[136:137]
	v_add_f32_dpp v74, v74, v74 row_half_mirror row_mask:0xf bank_mask:0xf bound_ctrl:1
	v_pk_fma_f32 v[198:199], v[14:15], v[138:139], v[198:199]
	v_add_f32_e32 v147, v198, v199
	v_add_f32_dpp v74, v74, v74 row_mirror row_mask:0xf bank_mask:0xf bound_ctrl:1
	v_pk_fma_f32 v[12:13], v[80:81], v[74:75], v[16:17] op_sel_hi:[1,0,1] neg_lo:[0,1,0] neg_hi:[0,1,0]
	v_pk_fma_f32 v[14:15], v[82:83], v[74:75], v[18:19] op_sel_hi:[1,0,1] neg_lo:[0,1,0] neg_hi:[0,1,0]
	v_pk_mul_f32 v[72:73], v[12:13], v[88:89]
	v_pk_fma_f32 v[72:73], v[14:15], v[90:91], v[72:73]
	ds_read_b128 v[76:79], v2 offset:2048
	v_add_f32_e32 v74, v72, v73
	ds_read_b128 v[84:87], v2 offset:18432
	ds_read_b128 v[80:83], v2 offset:10240
	v_add_f32_dpp v74, v74, v74 quad_perm:[1,0,3,2] row_mask:0xf bank_mask:0xf bound_ctrl:1
	ds_read_b128 v[136:139], v2 offset:26624
	ds_read_b128 v[24:27], v3 offset:32
	v_add_f32_dpp v74, v74, v74 quad_perm:[2,3,0,1] row_mask:0xf bank_mask:0xf bound_ctrl:1
	v_pk_fma_f32 v[16:17], v[28:29], v[96:97], v[12:13] op_sel:[1,0,0] op_sel_hi:[1,1,1]
	v_pk_fma_f32 v[18:19], v[28:29], v[98:99], v[14:15] op_sel:[1,0,0] op_sel_hi:[1,1,1]
	v_add_f32_dpp v74, v74, v74 row_half_mirror row_mask:0xf bank_mask:0xf bound_ctrl:1
	v_pk_mul_f32 v[198:199], v[12:13], v[140:141]
	v_pk_fma_f32 v[198:199], v[14:15], v[142:143], v[198:199]
	v_add_f32_dpp v74, v74, v74 row_mirror row_mask:0xf bank_mask:0xf bound_ctrl:1
	v_add_f32_e32 v148, v198, v199
	v_pk_fma_f32 v[12:13], v[92:93], v[74:75], v[16:17] op_sel_hi:[1,0,1] neg_lo:[0,1,0] neg_hi:[0,1,0]
	v_pk_fma_f32 v[14:15], v[94:95], v[74:75], v[18:19] op_sel_hi:[1,0,1] neg_lo:[0,1,0] neg_hi:[0,1,0]
	s_waitcnt lgkmcnt(6)
	v_pk_mul_f32 v[72:73], v[12:13], v[100:101]
	v_pk_fma_f32 v[72:73], v[14:15], v[102:103], v[72:73]
	ds_read_b128 v[88:91], v2 offset:2304
	v_add_f32_e32 v74, v72, v73
	ds_read_b128 v[96:99], v2 offset:18688
	ds_read_b128 v[92:95], v2 offset:10496
	v_add_f32_dpp v74, v74, v74 quad_perm:[1,0,3,2] row_mask:0xf bank_mask:0xf bound_ctrl:1
	ds_read_b128 v[140:143], v2 offset:26880
	v_pk_fma_f32 v[16:17], v[30:31], v[108:109], v[12:13] op_sel_hi:[0,1,1]
	v_add_f32_dpp v74, v74, v74 quad_perm:[2,3,0,1] row_mask:0xf bank_mask:0xf bound_ctrl:1
	v_pk_fma_f32 v[18:19], v[30:31], v[110:111], v[14:15] op_sel_hi:[0,1,1]
	v_pk_mul_f32 v[198:199], v[12:13], v[124:125]
	v_add_f32_dpp v74, v74, v74 row_half_mirror row_mask:0xf bank_mask:0xf bound_ctrl:1
	v_pk_fma_f32 v[198:199], v[14:15], v[126:127], v[198:199]
	v_add_f32_e32 v149, v198, v199
	v_add_f32_dpp v74, v74, v74 row_mirror row_mask:0xf bank_mask:0xf bound_ctrl:1
	v_pk_fma_f32 v[12:13], v[104:105], v[74:75], v[16:17] op_sel_hi:[1,0,1] neg_lo:[0,1,0] neg_hi:[0,1,0]
	v_pk_fma_f32 v[14:15], v[106:107], v[74:75], v[18:19] op_sel_hi:[1,0,1] neg_lo:[0,1,0] neg_hi:[0,1,0]
	v_pk_mul_f32 v[72:73], v[12:13], v[112:113]
	v_pk_fma_f32 v[72:73], v[14:15], v[114:115], v[72:73]
	ds_read_b128 v[100:103], v2 offset:2560
	v_add_f32_e32 v74, v72, v73
	ds_read_b128 v[108:111], v2 offset:18944
	ds_read_b128 v[104:107], v2 offset:10752
	v_add_f32_dpp v74, v74, v74 quad_perm:[1,0,3,2] row_mask:0xf bank_mask:0xf bound_ctrl:1
	ds_read_b128 v[124:127], v2 offset:27136
	v_pk_fma_f32 v[16:17], v[30:31], v[120:121], v[12:13] op_sel:[1,0,0] op_sel_hi:[1,1,1]
	v_add_f32_dpp v74, v74, v74 quad_perm:[2,3,0,1] row_mask:0xf bank_mask:0xf bound_ctrl:1
	v_pk_fma_f32 v[18:19], v[30:31], v[122:123], v[14:15] op_sel:[1,0,0] op_sel_hi:[1,1,1]
	v_pk_mul_f32 v[198:199], v[12:13], v[128:129]
	v_add_f32_dpp v74, v74, v74 row_half_mirror row_mask:0xf bank_mask:0xf bound_ctrl:1
	v_pk_fma_f32 v[198:199], v[14:15], v[130:131], v[198:199]
	v_add_f32_e32 v150, v198, v199
	v_add_f32_dpp v74, v74, v74 row_mirror row_mask:0xf bank_mask:0xf bound_ctrl:1
	v_pk_fma_f32 v[12:13], v[116:117], v[74:75], v[16:17] op_sel_hi:[1,0,1] neg_lo:[0,1,0] neg_hi:[0,1,0]
	v_pk_fma_f32 v[14:15], v[118:119], v[74:75], v[18:19] op_sel_hi:[1,0,1] neg_lo:[0,1,0] neg_hi:[0,1,0]
	s_waitcnt lgkmcnt(5)
; #define LAS __attribute__((address_space(3)))
; #define RW_LD(X, s) do { X.d = *(const LAS f32x4*)(bs + (s) * 256); X.k = *(const LAS f32x4*)(bs + 8192 + (s) * 256); X.a = *(const LAS f32x4*)(bs + 16384 + (s) * 256); \
;                          X.p = *(const LAS f32x4*)(bs + 24576 + (s) * 256); X.r = *(const LAS f32x4*)(bs + 32768 + (s) * 256); X.v = *(const LAS float*)(bv + (s) * 64); } while (0)
; #define RW_STEP(X, s) do { float sa = fmaf(S[3], X.k[3], fmaf(S[2], X.k[2], fmaf(S[1], X.k[1], S[0] * X.k[0]))); const f32x4 T = S * X.d + X.v * X.p; sa = -red16(sa); \
;                            S = T + sa * X.a; float y = fmaf(S[3], X.r[3], fmaf(S[2], X.r[2], fmaf(S[1], X.r[1], S[0] * X.r[0]))); y = red16(y); \
;                            yk = fmaf(selv[(s) & 15], y, yk); } while (0)
; #define RW_YST(s) do { if ((s) == 15) { ob[(size_t)(rowbase + c * 32 + seg) * D + 512 + h * 64 + vrow] = f2bf(yk); yk = 0.f; } } while (0)
; __device__ __forceinline__ void rwkv_scan(const Params& p, LAS unsigned char* lds, int rowbase, int T, int h, int q4, const float* S0, float* Sout) {
;     ...
;         if (comp) {
;             const LAS unsigned char* bs = b + seg * 16; const LAS unsigned char* bv = b + 40960 + vloc * 4;
;     ...
;             RwStep xa, xb, xc; float yk = 0.f;
;     ...
;             RW_LD(xa, 0); RW_LD(xb, 1);
; #pragma unroll
;             for (int s = 0; s < 30; s += 3) {
;                 RW_LD(xc, s + 2); RW_STEP(xa, s); RW_YST(s);
;                 RW_LD(xa, s + 3); RW_STEP(xb, s + 1); RW_YST(s + 1);
;                 RW_LD(xb, s + 4); RW_STEP(xc, s + 2); RW_YST(s + 2);
;             }
	v_pk_mul_f32 v[72:73], v[12:13], v[76:77]
	v_pk_fma_f32 v[72:73], v[14:15], v[78:79], v[72:73]
	ds_read_b128 v[112:115], v2 offset:2816
	v_add_f32_e32 v74, v72, v73
	ds_read_b128 v[120:123], v2 offset:19200
	ds_read_b128 v[116:119], v2 offset:11008
	v_add_f32_dpp v74, v74, v74 quad_perm:[1,0,3,2] row_mask:0xf bank_mask:0xf bound_ctrl:1
	ds_read_b128 v[128:131], v2 offset:27392
	v_pk_fma_f32 v[16:17], v[24:25], v[84:85], v[12:13] op_sel_hi:[0,1,1]
	v_add_f32_dpp v74, v74, v74 quad_perm:[2,3,0,1] row_mask:0xf bank_mask:0xf bound_ctrl:1
	v_pk_fma_f32 v[18:19], v[24:25], v[86:87], v[14:15] op_sel_hi:[0,1,1]
	v_pk_mul_f32 v[198:199], v[12:13], v[132:133]
	v_add_f32_dpp v74, v74, v74 row_half_mirror row_mask:0xf bank_mask:0xf bound_ctrl:1
	v_pk_fma_f32 v[198:199], v[14:15], v[134:135], v[198:199]
	v_add_f32_e32 v151, v198, v199
	v_add_f32_dpp v74, v74, v74 row_mirror row_mask:0xf bank_mask:0xf bound_ctrl:1
	v_pk_fma_f32 v[12:13], v[80:81], v[74:75], v[16:17] op_sel_hi:[1,0,1] neg_lo:[0,1,0] neg_hi:[0,1,0]
	v_pk_fma_f32 v[14:15], v[82:83], v[74:75], v[18:19] op_sel_hi:[1,0,1] neg_lo:[0,1,0] neg_hi:[0,1,0]
	v_pk_mul_f32 v[72:73], v[12:13], v[88:89]
	v_pk_fma_f32 v[72:73], v[14:15], v[90:91], v[72:73]
	ds_read_b128 v[76:79], v2 offset:3072
	v_add_f32_e32 v74, v72, v73
	ds_read_b128 v[84:87], v2 offset:19456
	ds_read_b128 v[80:83], v2 offset:11264
	v_add_f32_dpp v74, v74, v74 quad_perm:[1,0,3,2] row_mask:0xf bank_mask:0xf bound_ctrl:1
	ds_read_b128 v[132:135], v2 offset:27648
	ds_read_b128 v[28:31], v3 offset:48
	v_add_f32_dpp v74, v74, v74 quad_perm:[2,3,0,1] row_mask:0xf bank_mask:0xf bound_ctrl:1
	v_pk_fma_f32 v[16:17], v[24:25], v[96:97], v[12:13] op_sel:[1,0,0] op_sel_hi:[1,1,1]
	v_pk_fma_f32 v[18:19], v[24:25], v[98:99], v[14:15] op_sel:[1,0,0] op_sel_hi:[1,1,1]
	v_add_f32_dpp v74, v74, v74 row_half_mirror row_mask:0xf bank_mask:0xf bound_ctrl:1
	v_pk_mul_f32 v[198:199], v[12:13], v[136:137]
	v_pk_fma_f32 v[198:199], v[14:15], v[138:139], v[198:199]
	v_add_f32_dpp v74, v74, v74 row_mirror row_mask:0xf bank_mask:0xf bound_ctrl:1
	v_add_f32_e32 v152, v198, v199
	v_pk_fma_f32 v[12:13], v[92:93], v[74:75], v[16:17] op_sel_hi:[1,0,1] neg_lo:[0,1,0] neg_hi:[0,1,0]
	v_pk_fma_f32 v[14:15], v[94:95], v[74:75], v[18:19] op_sel_hi:[1,0,1] neg_lo:[0,1,0] neg_hi:[0,1,0]
	v_add_f32_dpp v176, v144, v144 row_mirror row_mask:0xf bank_mask:0x3
	s_waitcnt lgkmcnt(6)
	v_pk_mul_f32 v[72:73], v[12:13], v[100:101]
	v_add_f32_dpp v176, v152, v152 row_mirror row_mask:0xf bank_mask:0xc
	v_pk_fma_f32 v[72:73], v[14:15], v[102:103], v[72:73]
	ds_read_b128 v[88:91], v2 offset:3328
	v_add_f32_e32 v74, v72, v73
	ds_read_b128 v[96:99], v2 offset:19712
	ds_read_b128 v[92:95], v2 offset:11520
	v_add_f32_dpp v74, v74, v74 quad_perm:[1,0,3,2] row_mask:0xf bank_mask:0xf bound_ctrl:1
	ds_read_b128 v[136:139], v2 offset:27904
	v_pk_fma_f32 v[16:17], v[26:27], v[108:109], v[12:13] op_sel_hi:[0,1,1]
	v_add_f32_dpp v74, v74, v74 quad_perm:[2,3,0,1] row_mask:0xf bank_mask:0xf bound_ctrl:1
	v_pk_fma_f32 v[18:19], v[26:27], v[110:111], v[14:15] op_sel_hi:[0,1,1]
	v_pk_mul_f32 v[198:199], v[12:13], v[140:141]
	v_add_f32_dpp v74, v74, v74 row_half_mirror row_mask:0xf bank_mask:0xf bound_ctrl:1
	v_pk_fma_f32 v[198:199], v[14:15], v[142:143], v[198:199]
	v_add_f32_e32 v153, v198, v199
	v_add_f32_dpp v74, v74, v74 row_mirror row_mask:0xf bank_mask:0xf bound_ctrl:1
	v_pk_fma_f32 v[12:13], v[104:105], v[74:75], v[16:17] op_sel_hi:[1,0,1] neg_lo:[0,1,0] neg_hi:[0,1,0]
	v_pk_fma_f32 v[14:15], v[106:107], v[74:75], v[18:19] op_sel_hi:[1,0,1] neg_lo:[0,1,0] neg_hi:[0,1,0]
	v_add_f32_dpp v177, v145, v145 row_mirror row_mask:0xf bank_mask:0x3
	v_pk_mul_f32 v[72:73], v[12:13], v[112:113]
	s_nop 0
	v_add_f32_dpp v177, v153, v153 row_mirror row_mask:0xf bank_mask:0xc
	v_pk_fma_f32 v[72:73], v[14:15], v[114:115], v[72:73]
	ds_read_b128 v[100:103], v2 offset:3584
	v_add_f32_e32 v74, v72, v73
	ds_read_b128 v[108:111], v2 offset:19968
	ds_read_b128 v[104:107], v2 offset:11776
	v_add_f32_dpp v74, v74, v74 quad_perm:[1,0,3,2] row_mask:0xf bank_mask:0xf bound_ctrl:1
	ds_read_b128 v[140:143], v2 offset:28160
	v_pk_fma_f32 v[16:17], v[26:27], v[120:121], v[12:13] op_sel:[1,0,0] op_sel_hi:[1,1,1]
	v_add_f32_dpp v74, v74, v74 quad_perm:[2,3,0,1] row_mask:0xf bank_mask:0xf bound_ctrl:1
	v_pk_fma_f32 v[18:19], v[26:27], v[122:123], v[14:15] op_sel:[1,0,0] op_sel_hi:[1,1,1]
	v_pk_mul_f32 v[198:199], v[12:13], v[124:125]
	v_add_f32_dpp v74, v74, v74 row_half_mirror row_mask:0xf bank_mask:0xf bound_ctrl:1
	v_pk_fma_f32 v[198:199], v[14:15], v[126:127], v[198:199]
	v_add_f32_e32 v154, v198, v199
	v_add_f32_dpp v74, v74, v74 row_mirror row_mask:0xf bank_mask:0xf bound_ctrl:1
	v_pk_fma_f32 v[12:13], v[116:117], v[74:75], v[16:17] op_sel_hi:[1,0,1] neg_lo:[0,1,0] neg_hi:[0,1,0]
	v_pk_fma_f32 v[14:15], v[118:119], v[74:75], v[18:19] op_sel_hi:[1,0,1] neg_lo:[0,1,0] neg_hi:[0,1,0]
	v_add_f32_dpp v178, v146, v146 row_mirror row_mask:0xf bank_mask:0x3
	s_waitcnt lgkmcnt(5)
; #define LAS __attribute__((address_space(3)))
; #define RW_LD(X, s) do { X.d = *(const LAS f32x4*)(bs + (s) * 256); X.k = *(const LAS f32x4*)(bs + 8192 + (s) * 256); X.a = *(const LAS f32x4*)(bs + 16384 + (s) * 256); \
;                          X.p = *(const LAS f32x4*)(bs + 24576 + (s) * 256); X.r = *(const LAS f32x4*)(bs + 32768 + (s) * 256); X.v = *(const LAS float*)(bv + (s) * 64); } while (0)
; #define RW_STEP(X, s) do { float sa = fmaf(S[3], X.k[3], fmaf(S[2], X.k[2], fmaf(S[1], X.k[1], S[0] * X.k[0]))); const f32x4 T = S * X.d + X.v * X.p; sa = -red16(sa); \
;                            S = T + sa * X.a; float y = fmaf(S[3], X.r[3], fmaf(S[2], X.r[2], fmaf(S[1], X.r[1], S[0] * X.r[0]))); y = red16(y); \
;                            yk = fmaf(selv[(s) & 15], y, yk); } while (0)
; #define RW_YST(s) do { if ((s) == 15) { ob[(size_t)(rowbase + c * 32 + seg) * D + 512 + h * 64 + vrow] = f2bf(yk); yk = 0.f; } } while (0)
; __device__ __forceinline__ void rwkv_scan(const Params& p, LAS unsigned char* lds, int rowbase, int T, int h, int q4, const float* S0, float* Sout) {
;     ...
;         if (comp) {
;             const LAS unsigned char* bs = b + seg * 16; const LAS unsigned char* bv = b + 40960 + vloc * 4;
;     ...
;             RwStep xa, xb, xc; float yk = 0.f;
;     ...
;             RW_LD(xa, 0); RW_LD(xb, 1);
; #pragma unroll
;             for (int s = 0; s < 30; s += 3) {
;                 RW_LD(xc, s + 2); RW_STEP(xa, s); RW_YST(s);
;                 RW_LD(xa, s + 3); RW_STEP(xb, s + 1); RW_YST(s + 1);
;                 RW_LD(xb, s + 4); RW_STEP(xc, s + 2); RW_YST(s + 2);
;             }
	v_pk_mul_f32 v[72:73], v[12:13], v[76:77]
	v_add_f32_dpp v178, v154, v154 row_mirror row_mask:0xf bank_mask:0xc
	v_pk_fma_f32 v[72:73], v[14:15], v[78:79], v[72:73]
	ds_read_b128 v[112:115], v2 offset:3840
	v_add_f32_e32 v74, v72, v73
	ds_read_b128 v[120:123], v2 offset:20224
	ds_read_b128 v[116:119], v2 offset:12032
	v_add_f32_dpp v74, v74, v74 quad_perm:[1,0,3,2] row_mask:0xf bank_mask:0xf bound_ctrl:1
	ds_read_b128 v[124:127], v2 offset:28416
	v_pk_fma_f32 v[16:17], v[28:29], v[84:85], v[12:13] op_sel_hi:[0,1,1]
	v_add_f32_dpp v74, v74, v74 quad_perm:[2,3,0,1] row_mask:0xf bank_mask:0xf bound_ctrl:1
	v_pk_fma_f32 v[18:19], v[28:29], v[86:87], v[14:15] op_sel_hi:[0,1,1]
	v_pk_mul_f32 v[198:199], v[12:13], v[128:129]
	v_add_f32_dpp v74, v74, v74 row_half_mirror row_mask:0xf bank_mask:0xf bound_ctrl:1
	v_pk_fma_f32 v[198:199], v[14:15], v[130:131], v[198:199]
	v_add_f32_e32 v155, v198, v199
	v_add_f32_dpp v74, v74, v74 row_mirror row_mask:0xf bank_mask:0xf bound_ctrl:1
	v_pk_fma_f32 v[12:13], v[80:81], v[74:75], v[16:17] op_sel_hi:[1,0,1] neg_lo:[0,1,0] neg_hi:[0,1,0]
	v_pk_fma_f32 v[14:15], v[82:83], v[74:75], v[18:19] op_sel_hi:[1,0,1] neg_lo:[0,1,0] neg_hi:[0,1,0]
	v_add_f32_dpp v179, v147, v147 row_mirror row_mask:0xf bank_mask:0x3
	v_pk_mul_f32 v[72:73], v[12:13], v[88:89]
	s_nop 0
	v_add_f32_dpp v179, v155, v155 row_mirror row_mask:0xf bank_mask:0xc
	v_pk_fma_f32 v[72:73], v[14:15], v[90:91], v[72:73]
	ds_read_b128 v[76:79], v2 offset:4096
	v_add_f32_e32 v74, v72, v73
	ds_read_b128 v[84:87], v2 offset:20480
	ds_read_b128 v[80:83], v2 offset:12288
	v_add_f32_dpp v74, v74, v74 quad_perm:[1,0,3,2] row_mask:0xf bank_mask:0xf bound_ctrl:1
	ds_read_b128 v[128:131], v2 offset:28672
	ds_read_b128 v[24:27], v3 offset:64
	v_add_f32_dpp v74, v74, v74 quad_perm:[2,3,0,1] row_mask:0xf bank_mask:0xf bound_ctrl:1
	v_pk_fma_f32 v[16:17], v[28:29], v[96:97], v[12:13] op_sel:[1,0,0] op_sel_hi:[1,1,1]
	v_pk_fma_f32 v[18:19], v[28:29], v[98:99], v[14:15] op_sel:[1,0,0] op_sel_hi:[1,1,1]
	v_add_f32_dpp v74, v74, v74 row_half_mirror row_mask:0xf bank_mask:0xf bound_ctrl:1
	v_pk_mul_f32 v[198:199], v[12:13], v[132:133]
	v_pk_fma_f32 v[198:199], v[14:15], v[134:135], v[198:199]
	v_add_f32_dpp v74, v74, v74 row_mirror row_mask:0xf bank_mask:0xf bound_ctrl:1
	v_add_f32_e32 v156, v198, v199
	v_pk_fma_f32 v[12:13], v[92:93], v[74:75], v[16:17] op_sel_hi:[1,0,1] neg_lo:[0,1,0] neg_hi:[0,1,0]
	v_pk_fma_f32 v[14:15], v[94:95], v[74:75], v[18:19] op_sel_hi:[1,0,1] neg_lo:[0,1,0] neg_hi:[0,1,0]
	v_add_f32_dpp v180, v148, v148 row_mirror row_mask:0xf bank_mask:0x3
	s_waitcnt lgkmcnt(6)
	v_pk_mul_f32 v[72:73], v[12:13], v[100:101]
	v_add_f32_dpp v180, v156, v156 row_mirror row_mask:0xf bank_mask:0xc
	v_pk_fma_f32 v[72:73], v[14:15], v[102:103], v[72:73]
	ds_read_b128 v[88:91], v2 offset:4352
	v_add_f32_e32 v74, v72, v73
	ds_read_b128 v[96:99], v2 offset:20736
	ds_read_b128 v[92:95], v2 offset:12544
	v_add_f32_dpp v74, v74, v74 quad_perm:[1,0,3,2] row_mask:0xf bank_mask:0xf bound_ctrl:1
	ds_read_b128 v[132:135], v2 offset:28928
	v_pk_fma_f32 v[16:17], v[30:31], v[108:109], v[12:13] op_sel_hi:[0,1,1]
	v_add_f32_dpp v74, v74, v74 quad_perm:[2,3,0,1] row_mask:0xf bank_mask:0xf bound_ctrl:1
	v_pk_fma_f32 v[18:19], v[30:31], v[110:111], v[14:15] op_sel_hi:[0,1,1]
	v_pk_mul_f32 v[198:199], v[12:13], v[136:137]
	v_add_f32_dpp v74, v74, v74 row_half_mirror row_mask:0xf bank_mask:0xf bound_ctrl:1
	v_pk_fma_f32 v[198:199], v[14:15], v[138:139], v[198:199]
	v_add_f32_e32 v157, v198, v199
	v_add_f32_dpp v74, v74, v74 row_mirror row_mask:0xf bank_mask:0xf bound_ctrl:1
	v_pk_fma_f32 v[12:13], v[104:105], v[74:75], v[16:17] op_sel_hi:[1,0,1] neg_lo:[0,1,0] neg_hi:[0,1,0]
	v_pk_fma_f32 v[14:15], v[106:107], v[74:75], v[18:19] op_sel_hi:[1,0,1] neg_lo:[0,1,0] neg_hi:[0,1,0]
	v_add_f32_dpp v184, v176, v176 row_half_mirror row_mask:0xf bank_mask:0x5
	v_pk_mul_f32 v[72:73], v[12:13], v[112:113]
	s_nop 0
	v_add_f32_dpp v184, v180, v180 row_half_mirror row_mask:0xf bank_mask:0xa
	v_pk_fma_f32 v[72:73], v[14:15], v[114:115], v[72:73]
	ds_read_b128 v[100:103], v2 offset:4608
	v_add_f32_e32 v74, v72, v73
	ds_read_b128 v[108:111], v2 offset:20992
	ds_read_b128 v[104:107], v2 offset:12800
	v_add_f32_dpp v74, v74, v74 quad_perm:[1,0,3,2] row_mask:0xf bank_mask:0xf bound_ctrl:1
	ds_read_b128 v[136:139], v2 offset:29184
	v_pk_fma_f32 v[16:17], v[30:31], v[120:121], v[12:13] op_sel:[1,0,0] op_sel_hi:[1,1,1]
	v_add_f32_dpp v74, v74, v74 quad_perm:[2,3,0,1] row_mask:0xf bank_mask:0xf bound_ctrl:1
	v_pk_fma_f32 v[18:19], v[30:31], v[122:123], v[14:15] op_sel:[1,0,0] op_sel_hi:[1,1,1]
	v_pk_mul_f32 v[198:199], v[12:13], v[140:141]
	v_add_f32_dpp v74, v74, v74 row_half_mirror row_mask:0xf bank_mask:0xf bound_ctrl:1
	v_pk_fma_f32 v[198:199], v[14:15], v[142:143], v[198:199]
	v_add_f32_e32 v158, v198, v199
	v_add_f32_dpp v74, v74, v74 row_mirror row_mask:0xf bank_mask:0xf bound_ctrl:1
	v_pk_fma_f32 v[12:13], v[116:117], v[74:75], v[16:17] op_sel_hi:[1,0,1] neg_lo:[0,1,0] neg_hi:[0,1,0]
	v_pk_fma_f32 v[14:15], v[118:119], v[74:75], v[18:19] op_sel_hi:[1,0,1] neg_lo:[0,1,0] neg_hi:[0,1,0]
	v_add_f32_dpp v181, v149, v149 row_mirror row_mask:0xf bank_mask:0x3
	v_add_f32_dpp v185, v177, v177 row_half_mirror row_mask:0xf bank_mask:0x5
	s_waitcnt lgkmcnt(5)
; #define LAS __attribute__((address_space(3)))
; #define RW_LD(X, s) do { X.d = *(const LAS f32x4*)(bs + (s) * 256); X.k = *(const LAS f32x4*)(bs + 8192 + (s) * 256); X.a = *(const LAS f32x4*)(bs + 16384 + (s) * 256); \
;                          X.p = *(const LAS f32x4*)(bs + 24576 + (s) * 256); X.r = *(const LAS f32x4*)(bs + 32768 + (s) * 256); X.v = *(const LAS float*)(bv + (s) * 64); } while (0)
; #define RW_STEP(X, s) do { float sa = fmaf(S[3], X.k[3], fmaf(S[2], X.k[2], fmaf(S[1], X.k[1], S[0] * X.k[0]))); const f32x4 T = S * X.d + X.v * X.p; sa = -red16(sa); \
;                            S = T + sa * X.a; float y = fmaf(S[3], X.r[3], fmaf(S[2], X.r[2], fmaf(S[1], X.r[1], S[0] * X.r[0]))); y = red16(y); \
;                            yk = fmaf(selv[(s) & 15], y, yk); } while (0)
; #define RW_YST(s) do { if ((s) == 15) { ob[(size_t)(rowbase + c * 32 + seg) * D + 512 + h * 64 + vrow] = f2bf(yk); yk = 0.f; } } while (0)
; __device__ __forceinline__ void rwkv_scan(const Params& p, LAS unsigned char* lds, int rowbase, int T, int h, int q4, const float* S0, float* Sout) {
;     ...
;         if (comp) {
;             const LAS unsigned char* bs = b + seg * 16; const LAS unsigned char* bv = b + 40960 + vloc * 4;
;     ...
;             RwStep xa, xb, xc; float yk = 0.f;
;     ...
;             RW_LD(xa, 0); RW_LD(xb, 1);
; #pragma unroll
;             for (int s = 0; s < 30; s += 3) {
;                 RW_LD(xc, s + 2); RW_STEP(xa, s); RW_YST(s);
;                 RW_LD(xa, s + 3); RW_STEP(xb, s + 1); RW_YST(s + 1);
;                 RW_LD(xb, s + 4); RW_STEP(xc, s + 2); RW_YST(s + 2);
;             }
	v_add_f32_dpp v181, v157, v157 row_mirror row_mask:0xf bank_mask:0xc
	v_pk_mul_f32 v[72:73], v[12:13], v[76:77]
	v_pk_fma_f32 v[72:73], v[14:15], v[78:79], v[72:73]
	ds_read_b128 v[112:115], v2 offset:4864
	v_add_f32_e32 v74, v72, v73
	ds_read_b128 v[120:123], v2 offset:21248
	ds_read_b128 v[116:119], v2 offset:13056
	v_add_f32_dpp v74, v74, v74 quad_perm:[1,0,3,2] row_mask:0xf bank_mask:0xf bound_ctrl:1
	ds_read_b128 v[140:143], v2 offset:29440
	v_pk_fma_f32 v[16:17], v[24:25], v[84:85], v[12:13] op_sel_hi:[0,1,1]
	v_add_f32_dpp v74, v74, v74 quad_perm:[2,3,0,1] row_mask:0xf bank_mask:0xf bound_ctrl:1
	v_pk_fma_f32 v[18:19], v[24:25], v[86:87], v[14:15] op_sel_hi:[0,1,1]
	v_pk_mul_f32 v[198:199], v[12:13], v[124:125]
	v_add_f32_dpp v74, v74, v74 row_half_mirror row_mask:0xf bank_mask:0xf bound_ctrl:1
	v_pk_fma_f32 v[198:199], v[14:15], v[126:127], v[198:199]
	v_add_f32_e32 v159, v198, v199
	v_add_f32_dpp v74, v74, v74 row_mirror row_mask:0xf bank_mask:0xf bound_ctrl:1
	v_pk_fma_f32 v[12:13], v[80:81], v[74:75], v[16:17] op_sel_hi:[1,0,1] neg_lo:[0,1,0] neg_hi:[0,1,0]
	v_pk_fma_f32 v[14:15], v[82:83], v[74:75], v[18:19] op_sel_hi:[1,0,1] neg_lo:[0,1,0] neg_hi:[0,1,0]
	v_add_f32_dpp v185, v181, v181 row_half_mirror row_mask:0xf bank_mask:0xa
	v_add_f32_dpp v182, v150, v150 row_mirror row_mask:0xf bank_mask:0x3
	v_pk_mul_f32 v[72:73], v[12:13], v[88:89]
	s_nop 0
	v_add_f32_dpp v182, v158, v158 row_mirror row_mask:0xf bank_mask:0xc
	v_pk_fma_f32 v[72:73], v[14:15], v[90:91], v[72:73]
	ds_read_b128 v[76:79], v2 offset:5120
	v_add_f32_e32 v74, v72, v73
	ds_read_b128 v[84:87], v2 offset:21504
	ds_read_b128 v[80:83], v2 offset:13312
	v_add_f32_dpp v74, v74, v74 quad_perm:[1,0,3,2] row_mask:0xf bank_mask:0xf bound_ctrl:1
	ds_read_b128 v[124:127], v2 offset:29696
	ds_read_b128 v[28:31], v3 offset:80
	v_add_f32_dpp v74, v74, v74 quad_perm:[2,3,0,1] row_mask:0xf bank_mask:0xf bound_ctrl:1
	v_pk_fma_f32 v[16:17], v[24:25], v[96:97], v[12:13] op_sel:[1,0,0] op_sel_hi:[1,1,1]
	v_pk_fma_f32 v[18:19], v[24:25], v[98:99], v[14:15] op_sel:[1,0,0] op_sel_hi:[1,1,1]
	v_add_f32_dpp v74, v74, v74 row_half_mirror row_mask:0xf bank_mask:0xf bound_ctrl:1
	v_pk_mul_f32 v[198:199], v[12:13], v[128:129]
	v_pk_fma_f32 v[198:199], v[14:15], v[130:131], v[198:199]
	v_add_f32_dpp v74, v74, v74 row_mirror row_mask:0xf bank_mask:0xf bound_ctrl:1
	v_add_f32_e32 v160, v198, v199
	v_pk_fma_f32 v[12:13], v[92:93], v[74:75], v[16:17] op_sel_hi:[1,0,1] neg_lo:[0,1,0] neg_hi:[0,1,0]
	v_pk_fma_f32 v[14:15], v[94:95], v[74:75], v[18:19] op_sel_hi:[1,0,1] neg_lo:[0,1,0] neg_hi:[0,1,0]
	v_add_f32_dpp v186, v178, v178 row_half_mirror row_mask:0xf bank_mask:0x5
	s_nop 1
	v_add_f32_dpp v186, v182, v182 row_half_mirror row_mask:0xf bank_mask:0xa
	v_cndmask_b32_e64 v190, v184, v186, s[98:99]
	s_waitcnt lgkmcnt(6)
	v_pk_mul_f32 v[72:73], v[12:13], v[100:101]
	v_pk_fma_f32 v[72:73], v[14:15], v[102:103], v[72:73]
	ds_read_b128 v[88:91], v2 offset:5376
	v_add_f32_e32 v74, v72, v73
	ds_read_b128 v[96:99], v2 offset:21760
	ds_read_b128 v[92:95], v2 offset:13568
	v_add_f32_dpp v74, v74, v74 quad_perm:[1,0,3,2] row_mask:0xf bank_mask:0xf bound_ctrl:1
	ds_read_b128 v[128:131], v2 offset:29952
	v_pk_fma_f32 v[16:17], v[26:27], v[108:109], v[12:13] op_sel_hi:[0,1,1]
	v_add_f32_dpp v74, v74, v74 quad_perm:[2,3,0,1] row_mask:0xf bank_mask:0xf bound_ctrl:1
	v_pk_fma_f32 v[18:19], v[26:27], v[110:111], v[14:15] op_sel_hi:[0,1,1]
	v_pk_mul_f32 v[198:199], v[12:13], v[132:133]
	v_add_f32_dpp v74, v74, v74 row_half_mirror row_mask:0xf bank_mask:0xf bound_ctrl:1
	v_pk_fma_f32 v[198:199], v[14:15], v[134:135], v[198:199]
	v_add_f32_e32 v161, v198, v199
	v_add_f32_dpp v74, v74, v74 row_mirror row_mask:0xf bank_mask:0xf bound_ctrl:1
	v_pk_fma_f32 v[12:13], v[104:105], v[74:75], v[16:17] op_sel_hi:[1,0,1] neg_lo:[0,1,0] neg_hi:[0,1,0]
	v_pk_fma_f32 v[14:15], v[106:107], v[74:75], v[18:19] op_sel_hi:[1,0,1] neg_lo:[0,1,0] neg_hi:[0,1,0]
	v_cndmask_b32_e64 v191, v186, v184, s[98:99]
	v_add_f32_dpp v183, v151, v151 row_mirror row_mask:0xf bank_mask:0x3
	s_nop 0
	v_add_f32_dpp v188, v191, v190 quad_perm:[2,3,0,1] row_mask:0xf bank_mask:0xf
	v_pk_mul_f32 v[72:73], v[12:13], v[112:113]
	v_pk_fma_f32 v[72:73], v[14:15], v[114:115], v[72:73]
	ds_read_b128 v[100:103], v2 offset:5632
	v_add_f32_e32 v74, v72, v73
	ds_read_b128 v[108:111], v2 offset:22016
	ds_read_b128 v[104:107], v2 offset:13824
	v_add_f32_dpp v74, v74, v74 quad_perm:[1,0,3,2] row_mask:0xf bank_mask:0xf bound_ctrl:1
	ds_read_b128 v[132:135], v2 offset:30208
	v_pk_fma_f32 v[16:17], v[26:27], v[120:121], v[12:13] op_sel:[1,0,0] op_sel_hi:[1,1,1]
	v_add_f32_dpp v74, v74, v74 quad_perm:[2,3,0,1] row_mask:0xf bank_mask:0xf bound_ctrl:1
	v_pk_fma_f32 v[18:19], v[26:27], v[122:123], v[14:15] op_sel:[1,0,0] op_sel_hi:[1,1,1]
	v_pk_mul_f32 v[198:199], v[12:13], v[136:137]
	v_add_f32_dpp v74, v74, v74 row_half_mirror row_mask:0xf bank_mask:0xf bound_ctrl:1
	v_pk_fma_f32 v[198:199], v[14:15], v[138:139], v[198:199]
	v_add_f32_e32 v162, v198, v199
	v_add_f32_dpp v74, v74, v74 row_mirror row_mask:0xf bank_mask:0xf bound_ctrl:1
	v_pk_fma_f32 v[12:13], v[116:117], v[74:75], v[16:17] op_sel_hi:[1,0,1] neg_lo:[0,1,0] neg_hi:[0,1,0]
	v_pk_fma_f32 v[14:15], v[118:119], v[74:75], v[18:19] op_sel_hi:[1,0,1] neg_lo:[0,1,0] neg_hi:[0,1,0]
	v_add_f32_dpp v183, v159, v159 row_mirror row_mask:0xf bank_mask:0xc
	v_add_f32_dpp v187, v179, v179 row_half_mirror row_mask:0xf bank_mask:0x5
	s_waitcnt lgkmcnt(5)
; #define LAS __attribute__((address_space(3)))
; #define RW_LD(X, s) do { X.d = *(const LAS f32x4*)(bs + (s) * 256); X.k = *(const LAS f32x4*)(bs + 8192 + (s) * 256); X.a = *(const LAS f32x4*)(bs + 16384 + (s) * 256); \
;                          X.p = *(const LAS f32x4*)(bs + 24576 + (s) * 256); X.r = *(const LAS f32x4*)(bs + 32768 + (s) * 256); X.v = *(const LAS float*)(bv + (s) * 64); } while (0)
; #define RW_STEP(X, s) do { float sa = fmaf(S[3], X.k[3], fmaf(S[2], X.k[2], fmaf(S[1], X.k[1], S[0] * X.k[0]))); const f32x4 T = S * X.d + X.v * X.p; sa = -red16(sa); \
;                            S = T + sa * X.a; float y = fmaf(S[3], X.r[3], fmaf(S[2], X.r[2], fmaf(S[1], X.r[1], S[0] * X.r[0]))); y = red16(y); \
;                            yk = fmaf(selv[(s) & 15], y, yk); } while (0)
; #define RW_YST(s) do { if ((s) == 15) { ob[(size_t)(rowbase + c * 32 + seg) * D + 512 + h * 64 + vrow] = f2bf(yk); yk = 0.f; } } while (0)
; __device__ __forceinline__ void rwkv_scan(const Params& p, LAS unsigned char* lds, int rowbase, int T, int h, int q4, const float* S0, float* Sout) {
;     ...
;         if (comp) {
;             const LAS unsigned char* bs = b + seg * 16; const LAS unsigned char* bv = b + 40960 + vloc * 4;
;     ...
;             RwStep xa, xb, xc; float yk = 0.f;
;     ...
;             RW_LD(xa, 0); RW_LD(xb, 1);
; #pragma unroll
;             for (int s = 0; s < 30; s += 3) {
;                 RW_LD(xc, s + 2); RW_STEP(xa, s); RW_YST(s);
;                 RW_LD(xa, s + 3); RW_STEP(xb, s + 1); RW_YST(s + 1);
;                 RW_LD(xb, s + 4); RW_STEP(xc, s + 2); RW_YST(s + 2);
;             }
	v_pk_mul_f32 v[72:73], v[12:13], v[76:77]
	v_add_f32_dpp v187, v183, v183 row_half_mirror row_mask:0xf bank_mask:0xa
	v_pk_fma_f32 v[72:73], v[14:15], v[78:79], v[72:73]
	ds_read_b128 v[112:115], v2 offset:5888
	v_add_f32_e32 v74, v72, v73
	ds_read_b128 v[120:123], v2 offset:22272
	ds_read_b128 v[116:119], v2 offset:14080
	v_add_f32_dpp v74, v74, v74 quad_perm:[1,0,3,2] row_mask:0xf bank_mask:0xf bound_ctrl:1
	ds_read_b128 v[136:139], v2 offset:30464
	v_pk_fma_f32 v[16:17], v[28:29], v[84:85], v[12:13] op_sel_hi:[0,1,1]
	v_add_f32_dpp v74, v74, v74 quad_perm:[2,3,0,1] row_mask:0xf bank_mask:0xf bound_ctrl:1
	v_pk_fma_f32 v[18:19], v[28:29], v[86:87], v[14:15] op_sel_hi:[0,1,1]
	v_pk_mul_f32 v[198:199], v[12:13], v[140:141]
	v_add_f32_dpp v74, v74, v74 row_half_mirror row_mask:0xf bank_mask:0xf bound_ctrl:1
	v_pk_fma_f32 v[198:199], v[14:15], v[142:143], v[198:199]
	v_add_f32_e32 v163, v198, v199
	v_add_f32_dpp v74, v74, v74 row_mirror row_mask:0xf bank_mask:0xf bound_ctrl:1
	v_pk_fma_f32 v[12:13], v[80:81], v[74:75], v[16:17] op_sel_hi:[1,0,1] neg_lo:[0,1,0] neg_hi:[0,1,0]
	v_pk_fma_f32 v[14:15], v[82:83], v[74:75], v[18:19] op_sel_hi:[1,0,1] neg_lo:[0,1,0] neg_hi:[0,1,0]
	v_cndmask_b32_e64 v190, v185, v187, s[98:99]
	v_cndmask_b32_e64 v191, v187, v185, s[98:99]
	v_pk_mul_f32 v[72:73], v[12:13], v[88:89]
	s_nop 0
	v_add_f32_dpp v189, v191, v190 quad_perm:[2,3,0,1] row_mask:0xf bank_mask:0xf
	v_pk_fma_f32 v[72:73], v[14:15], v[90:91], v[72:73]
	ds_read_b128 v[76:79], v2 offset:6144
	v_add_f32_e32 v74, v72, v73
	ds_read_b128 v[84:87], v2 offset:22528
	ds_read_b128 v[80:83], v2 offset:14336
	v_add_f32_dpp v74, v74, v74 quad_perm:[1,0,3,2] row_mask:0xf bank_mask:0xf bound_ctrl:1
	ds_read_b128 v[140:143], v2 offset:30720
	ds_read_b128 v[24:27], v3 offset:96
	v_add_f32_dpp v74, v74, v74 quad_perm:[2,3,0,1] row_mask:0xf bank_mask:0xf bound_ctrl:1
	v_pk_fma_f32 v[16:17], v[28:29], v[96:97], v[12:13] op_sel:[1,0,0] op_sel_hi:[1,1,1]
	v_pk_fma_f32 v[18:19], v[28:29], v[98:99], v[14:15] op_sel:[1,0,0] op_sel_hi:[1,1,1]
	v_add_f32_dpp v74, v74, v74 row_half_mirror row_mask:0xf bank_mask:0xf bound_ctrl:1
	v_pk_mul_f32 v[198:199], v[12:13], v[124:125]
	v_pk_fma_f32 v[198:199], v[14:15], v[126:127], v[198:199]
	v_add_f32_dpp v74, v74, v74 row_mirror row_mask:0xf bank_mask:0xf bound_ctrl:1
	v_add_f32_e32 v164, v198, v199
	v_pk_fma_f32 v[12:13], v[92:93], v[74:75], v[16:17] op_sel_hi:[1,0,1] neg_lo:[0,1,0] neg_hi:[0,1,0]
	v_pk_fma_f32 v[14:15], v[94:95], v[74:75], v[18:19] op_sel_hi:[1,0,1] neg_lo:[0,1,0] neg_hi:[0,1,0]
	v_cndmask_b32_e64 v190, v188, v189, s[100:101]
	v_cndmask_b32_e64 v191, v189, v188, s[100:101]
	s_waitcnt lgkmcnt(6)
	v_pk_mul_f32 v[72:73], v[12:13], v[100:101]
	v_add_f32_dpp v192, v191, v190 quad_perm:[1,0,3,2] row_mask:0xf bank_mask:0xf
	v_pk_fma_f32 v[72:73], v[14:15], v[102:103], v[72:73]
	ds_read_b128 v[88:91], v2 offset:6400
	v_add_f32_e32 v74, v72, v73
	ds_read_b128 v[96:99], v2 offset:22784
	ds_read_b128 v[92:95], v2 offset:14592
	v_add_f32_dpp v74, v74, v74 quad_perm:[1,0,3,2] row_mask:0xf bank_mask:0xf bound_ctrl:1
	ds_read_b128 v[124:127], v2 offset:30976
	v_pk_fma_f32 v[16:17], v[30:31], v[108:109], v[12:13] op_sel_hi:[0,1,1]
	v_add_f32_dpp v74, v74, v74 quad_perm:[2,3,0,1] row_mask:0xf bank_mask:0xf bound_ctrl:1
	v_pk_fma_f32 v[18:19], v[30:31], v[110:111], v[14:15] op_sel_hi:[0,1,1]
	v_pk_mul_f32 v[198:199], v[12:13], v[128:129]
	v_add_f32_dpp v74, v74, v74 row_half_mirror row_mask:0xf bank_mask:0xf bound_ctrl:1
	v_pk_fma_f32 v[198:199], v[14:15], v[130:131], v[198:199]
	v_add_f32_e32 v165, v198, v199
	v_add_f32_dpp v74, v74, v74 row_mirror row_mask:0xf bank_mask:0xf bound_ctrl:1
	v_pk_fma_f32 v[12:13], v[104:105], v[74:75], v[16:17] op_sel_hi:[1,0,1] neg_lo:[0,1,0] neg_hi:[0,1,0]
	v_pk_fma_f32 v[14:15], v[106:107], v[74:75], v[18:19] op_sel_hi:[1,0,1] neg_lo:[0,1,0] neg_hi:[0,1,0]
	v_lshlrev_b32_e32 v194, 11, v5
	v_mov_b32_e32 v195, 0
	v_pk_mul_f32 v[72:73], v[12:13], v[112:113]
	v_pk_fma_f32 v[72:73], v[14:15], v[114:115], v[72:73]
	ds_read_b128 v[100:103], v2 offset:6656
	v_add_f32_e32 v74, v72, v73
	ds_read_b128 v[108:111], v2 offset:23040
	ds_read_b128 v[104:107], v2 offset:14848
	v_add_f32_dpp v74, v74, v74 quad_perm:[1,0,3,2] row_mask:0xf bank_mask:0xf bound_ctrl:1
	ds_read_b128 v[128:131], v2 offset:31232
	v_pk_fma_f32 v[16:17], v[30:31], v[120:121], v[12:13] op_sel:[1,0,0] op_sel_hi:[1,1,1]
	v_add_f32_dpp v74, v74, v74 quad_perm:[2,3,0,1] row_mask:0xf bank_mask:0xf bound_ctrl:1
	v_pk_fma_f32 v[18:19], v[30:31], v[122:123], v[14:15] op_sel:[1,0,0] op_sel_hi:[1,1,1]
	v_pk_mul_f32 v[198:199], v[12:13], v[132:133]
	v_add_f32_dpp v74, v74, v74 row_half_mirror row_mask:0xf bank_mask:0xf bound_ctrl:1
	v_pk_fma_f32 v[198:199], v[14:15], v[134:135], v[198:199]
	v_add_f32_e32 v166, v198, v199
	v_add_f32_dpp v74, v74, v74 row_mirror row_mask:0xf bank_mask:0xf bound_ctrl:1
	v_pk_fma_f32 v[12:13], v[116:117], v[74:75], v[16:17] op_sel_hi:[1,0,1] neg_lo:[0,1,0] neg_hi:[0,1,0]
	v_pk_fma_f32 v[14:15], v[118:119], v[74:75], v[18:19] op_sel_hi:[1,0,1] neg_lo:[0,1,0] neg_hi:[0,1,0]
	v_cvt_pk_bf16_f32 v193, v192, v192
	v_lshl_add_u64 v[194:195], v[6:7], 0, v[194:195]
	s_waitcnt lgkmcnt(5)
; #define LAS __attribute__((address_space(3)))
; #define RW_LD(X, s) do { X.d = *(const LAS f32x4*)(bs + (s) * 256); X.k = *(const LAS f32x4*)(bs + 8192 + (s) * 256); X.a = *(const LAS f32x4*)(bs + 16384 + (s) * 256); \
;                          X.p = *(const LAS f32x4*)(bs + 24576 + (s) * 256); X.r = *(const LAS f32x4*)(bs + 32768 + (s) * 256); X.v = *(const LAS float*)(bv + (s) * 64); } while (0)
; #define RW_STEP(X, s) do { float sa = fmaf(S[3], X.k[3], fmaf(S[2], X.k[2], fmaf(S[1], X.k[1], S[0] * X.k[0]))); const f32x4 T = S * X.d + X.v * X.p; sa = -red16(sa); \
;                            S = T + sa * X.a; float y = fmaf(S[3], X.r[3], fmaf(S[2], X.r[2], fmaf(S[1], X.r[1], S[0] * X.r[0]))); y = red16(y); \
;                            yk = fmaf(selv[(s) & 15], y, yk); } while (0)
; #define RW_YST(s) do { if ((s) == 15) { ob[(size_t)(rowbase + c * 32 + seg) * D + 512 + h * 64 + vrow] = f2bf(yk); yk = 0.f; } } while (0)
; __device__ __forceinline__ void rwkv_scan(const Params& p, LAS unsigned char* lds, int rowbase, int T, int h, int q4, const float* S0, float* Sout) {
;     ...
;         if (comp) {
;             const LAS unsigned char* bs = b + seg * 16; const LAS unsigned char* bv = b + 40960 + vloc * 4;
;     ...
;             RwStep xa, xb, xc; float yk = 0.f;
;     ...
;             RW_LD(xa, 0); RW_LD(xb, 1);
; #pragma unroll
;             for (int s = 0; s < 30; s += 3) {
;                 RW_LD(xc, s + 2); RW_STEP(xa, s); RW_YST(s);
;                 RW_LD(xa, s + 3); RW_STEP(xb, s + 1); RW_YST(s + 1);
;                 RW_LD(xb, s + 4); RW_STEP(xc, s + 2); RW_YST(s + 2);
;             }
	v_pk_mul_f32 v[72:73], v[12:13], v[76:77]
	v_pk_fma_f32 v[72:73], v[14:15], v[78:79], v[72:73]
	ds_read_b128 v[112:115], v2 offset:6912
	v_add_f32_e32 v74, v72, v73
	ds_read_b128 v[120:123], v2 offset:23296
	ds_read_b128 v[116:119], v2 offset:15104
	v_add_f32_dpp v74, v74, v74 quad_perm:[1,0,3,2] row_mask:0xf bank_mask:0xf bound_ctrl:1
	ds_read_b128 v[132:135], v2 offset:31488
	v_pk_fma_f32 v[16:17], v[24:25], v[84:85], v[12:13] op_sel_hi:[0,1,1]
	v_add_f32_dpp v74, v74, v74 quad_perm:[2,3,0,1] row_mask:0xf bank_mask:0xf bound_ctrl:1
	v_pk_fma_f32 v[18:19], v[24:25], v[86:87], v[14:15] op_sel_hi:[0,1,1]
	v_pk_mul_f32 v[198:199], v[12:13], v[136:137]
	v_add_f32_dpp v74, v74, v74 row_half_mirror row_mask:0xf bank_mask:0xf bound_ctrl:1
	v_pk_fma_f32 v[198:199], v[14:15], v[138:139], v[198:199]
	v_add_f32_e32 v167, v198, v199
	v_add_f32_dpp v74, v74, v74 row_mirror row_mask:0xf bank_mask:0xf bound_ctrl:1
	v_pk_fma_f32 v[12:13], v[80:81], v[74:75], v[16:17] op_sel_hi:[1,0,1] neg_lo:[0,1,0] neg_hi:[0,1,0]
	v_pk_fma_f32 v[14:15], v[82:83], v[74:75], v[18:19] op_sel_hi:[1,0,1] neg_lo:[0,1,0] neg_hi:[0,1,0]
	global_store_short v[194:195], v193, off offset:1024
	v_pk_mul_f32 v[72:73], v[12:13], v[88:89]
	v_pk_fma_f32 v[72:73], v[14:15], v[90:91], v[72:73]
	ds_read_b128 v[76:79], v2 offset:7168
	v_add_f32_e32 v74, v72, v73
	ds_read_b128 v[84:87], v2 offset:23552
	ds_read_b128 v[80:83], v2 offset:15360
	v_add_f32_dpp v74, v74, v74 quad_perm:[1,0,3,2] row_mask:0xf bank_mask:0xf bound_ctrl:1
	ds_read_b128 v[136:139], v2 offset:31744
	ds_read_b128 v[28:31], v3 offset:112
	v_add_f32_dpp v74, v74, v74 quad_perm:[2,3,0,1] row_mask:0xf bank_mask:0xf bound_ctrl:1
	v_pk_fma_f32 v[16:17], v[24:25], v[96:97], v[12:13] op_sel:[1,0,0] op_sel_hi:[1,1,1]
	v_pk_fma_f32 v[18:19], v[24:25], v[98:99], v[14:15] op_sel:[1,0,0] op_sel_hi:[1,1,1]
	v_add_f32_dpp v74, v74, v74 row_half_mirror row_mask:0xf bank_mask:0xf bound_ctrl:1
	v_pk_mul_f32 v[198:199], v[12:13], v[140:141]
	v_pk_fma_f32 v[198:199], v[14:15], v[142:143], v[198:199]
	v_add_f32_dpp v74, v74, v74 row_mirror row_mask:0xf bank_mask:0xf bound_ctrl:1
	v_add_f32_e32 v168, v198, v199
	v_pk_fma_f32 v[12:13], v[92:93], v[74:75], v[16:17] op_sel_hi:[1,0,1] neg_lo:[0,1,0] neg_hi:[0,1,0]
	v_pk_fma_f32 v[14:15], v[94:95], v[74:75], v[18:19] op_sel_hi:[1,0,1] neg_lo:[0,1,0] neg_hi:[0,1,0]
	v_add_f32_dpp v176, v160, v160 row_mirror row_mask:0xf bank_mask:0x3
	s_waitcnt lgkmcnt(6)
	v_pk_mul_f32 v[72:73], v[12:13], v[100:101]
	v_add_f32_dpp v176, v168, v168 row_mirror row_mask:0xf bank_mask:0xc
	v_pk_fma_f32 v[72:73], v[14:15], v[102:103], v[72:73]
	ds_read_b128 v[88:91], v2 offset:7424
	v_add_f32_e32 v74, v72, v73
	ds_read_b128 v[96:99], v2 offset:23808
	ds_read_b128 v[92:95], v2 offset:15616
	v_add_f32_dpp v74, v74, v74 quad_perm:[1,0,3,2] row_mask:0xf bank_mask:0xf bound_ctrl:1
	ds_read_b128 v[140:143], v2 offset:32000
	v_pk_fma_f32 v[16:17], v[26:27], v[108:109], v[12:13] op_sel_hi:[0,1,1]
	v_add_f32_dpp v74, v74, v74 quad_perm:[2,3,0,1] row_mask:0xf bank_mask:0xf bound_ctrl:1
	v_pk_fma_f32 v[18:19], v[26:27], v[110:111], v[14:15] op_sel_hi:[0,1,1]
	v_pk_mul_f32 v[198:199], v[12:13], v[124:125]
	v_add_f32_dpp v74, v74, v74 row_half_mirror row_mask:0xf bank_mask:0xf bound_ctrl:1
	v_pk_fma_f32 v[198:199], v[14:15], v[126:127], v[198:199]
	v_add_f32_e32 v169, v198, v199
	v_add_f32_dpp v74, v74, v74 row_mirror row_mask:0xf bank_mask:0xf bound_ctrl:1
	v_pk_fma_f32 v[12:13], v[104:105], v[74:75], v[16:17] op_sel_hi:[1,0,1] neg_lo:[0,1,0] neg_hi:[0,1,0]
	v_pk_fma_f32 v[14:15], v[106:107], v[74:75], v[18:19] op_sel_hi:[1,0,1] neg_lo:[0,1,0] neg_hi:[0,1,0]
	v_add_f32_dpp v177, v161, v161 row_mirror row_mask:0xf bank_mask:0x3
	v_pk_mul_f32 v[72:73], v[12:13], v[112:113]
	s_nop 0
	v_add_f32_dpp v177, v169, v169 row_mirror row_mask:0xf bank_mask:0xc
	v_pk_fma_f32 v[72:73], v[14:15], v[114:115], v[72:73]
	ds_read_b128 v[100:103], v2 offset:7680
	v_add_f32_e32 v74, v72, v73
	ds_read_b128 v[108:111], v2 offset:24064
	ds_read_b128 v[104:107], v2 offset:15872
	v_add_f32_dpp v74, v74, v74 quad_perm:[1,0,3,2] row_mask:0xf bank_mask:0xf bound_ctrl:1
	ds_read_b128 v[124:127], v2 offset:32256
	v_pk_fma_f32 v[16:17], v[26:27], v[120:121], v[12:13] op_sel:[1,0,0] op_sel_hi:[1,1,1]
	v_add_f32_dpp v74, v74, v74 quad_perm:[2,3,0,1] row_mask:0xf bank_mask:0xf bound_ctrl:1
	v_pk_fma_f32 v[18:19], v[26:27], v[122:123], v[14:15] op_sel:[1,0,0] op_sel_hi:[1,1,1]
	v_pk_mul_f32 v[198:199], v[12:13], v[128:129]
	v_add_f32_dpp v74, v74, v74 row_half_mirror row_mask:0xf bank_mask:0xf bound_ctrl:1
	v_pk_fma_f32 v[198:199], v[14:15], v[130:131], v[198:199]
	v_add_f32_e32 v170, v198, v199
	v_add_f32_dpp v74, v74, v74 row_mirror row_mask:0xf bank_mask:0xf bound_ctrl:1
	v_pk_fma_f32 v[12:13], v[116:117], v[74:75], v[16:17] op_sel_hi:[1,0,1] neg_lo:[0,1,0] neg_hi:[0,1,0]
	v_pk_fma_f32 v[14:15], v[118:119], v[74:75], v[18:19] op_sel_hi:[1,0,1] neg_lo:[0,1,0] neg_hi:[0,1,0]
	v_add_f32_dpp v178, v162, v162 row_mirror row_mask:0xf bank_mask:0x3
	s_waitcnt lgkmcnt(5)
; __device__ __forceinline__ bf16_t f2bf(float f) { return (bf16_t)(cvt_pk_bf16(f, 0.f) & 0xffffu); }
; #define RW_LD(X, s) do { X.d = *(const LAS f32x4*)(bs + (s) * 256); X.k = *(const LAS f32x4*)(bs + 8192 + (s) * 256); X.a = *(const LAS f32x4*)(bs + 16384 + (s) * 256); \
;                          X.p = *(const LAS f32x4*)(bs + 24576 + (s) * 256); X.r = *(const LAS f32x4*)(bs + 32768 + (s) * 256); X.v = *(const LAS float*)(bv + (s) * 64); } while (0)
; #define RW_STEP(X, s) do { float sa = fmaf(S[3], X.k[3], fmaf(S[2], X.k[2], fmaf(S[1], X.k[1], S[0] * X.k[0]))); const f32x4 T = S * X.d + X.v * X.p; sa = -red16(sa); \
;                            S = T + sa * X.a; float y = fmaf(S[3], X.r[3], fmaf(S[2], X.r[2], fmaf(S[1], X.r[1], S[0] * X.r[0]))); y = red16(y); \
;                            yk = fmaf(selv[(s) & 15], y, yk); } while (0)
; #define RW_YST(s) do { if ((s) == 15) { ob[(size_t)(rowbase + c * 32 + seg) * D + 512 + h * 64 + vrow] = f2bf(yk); yk = 0.f; } } while (0)
; __device__ __forceinline__ void rwkv_scan(const Params& p, LAS unsigned char* lds, int rowbase, int T, int h, int q4, const float* S0, float* Sout) {
;     ...
;             RwStep xa, xb, xc; float yk = 0.f;
;     ...
;             RW_LD(xa, 0); RW_LD(xb, 1);
; #pragma unroll
;             for (int s = 0; s < 30; s += 3) {
;                 RW_LD(xc, s + 2); RW_STEP(xa, s); RW_YST(s);
;                 RW_LD(xa, s + 3); RW_STEP(xb, s + 1); RW_YST(s + 1);
;                 RW_LD(xb, s + 4); RW_STEP(xc, s + 2); RW_YST(s + 2);
;             }
;             RW_STEP(xa, 30); RW_STEP(xb, 31);
;             ob[(size_t)(rowbase + c * 32 + 16 + seg) * D + 512 + h * 64 + vrow] = f2bf(yk);
;     ...
;         }
;     }
;     if (comp) *(f32x4*)(Sout + vrow * 64 + seg * 4) = S;
	v_pk_mul_f32 v[72:73], v[12:13], v[76:77]
	v_add_f32_dpp v178, v170, v170 row_mirror row_mask:0xf bank_mask:0xc
	v_pk_fma_f32 v[72:73], v[14:15], v[78:79], v[72:73]
	ds_read_b128 v[112:115], v2 offset:7936
	v_add_f32_e32 v74, v72, v73
	ds_read_b128 v[120:123], v2 offset:24320
	ds_read_b128 v[116:119], v2 offset:16128
	v_add_f32_dpp v74, v74, v74 quad_perm:[1,0,3,2] row_mask:0xf bank_mask:0xf bound_ctrl:1
	ds_read_b128 v[128:131], v2 offset:32512
	v_pk_fma_f32 v[16:17], v[28:29], v[84:85], v[12:13] op_sel_hi:[0,1,1]
	v_add_f32_dpp v74, v74, v74 quad_perm:[2,3,0,1] row_mask:0xf bank_mask:0xf bound_ctrl:1
	v_pk_fma_f32 v[18:19], v[28:29], v[86:87], v[14:15] op_sel_hi:[0,1,1]
	v_pk_mul_f32 v[198:199], v[12:13], v[132:133]
	v_add_f32_dpp v74, v74, v74 row_half_mirror row_mask:0xf bank_mask:0xf bound_ctrl:1
	v_pk_fma_f32 v[198:199], v[14:15], v[134:135], v[198:199]
	v_add_f32_e32 v171, v198, v199
	v_add_f32_dpp v74, v74, v74 row_mirror row_mask:0xf bank_mask:0xf bound_ctrl:1
	v_pk_fma_f32 v[12:13], v[80:81], v[74:75], v[16:17] op_sel_hi:[1,0,1] neg_lo:[0,1,0] neg_hi:[0,1,0]
	v_pk_fma_f32 v[14:15], v[82:83], v[74:75], v[18:19] op_sel_hi:[1,0,1] neg_lo:[0,1,0] neg_hi:[0,1,0]
	v_add_f32_dpp v179, v163, v163 row_mirror row_mask:0xf bank_mask:0x3
	v_pk_mul_f32 v[72:73], v[12:13], v[88:89]
	s_nop 0
	v_add_f32_dpp v179, v171, v171 row_mirror row_mask:0xf bank_mask:0xc
	v_pk_fma_f32 v[72:73], v[14:15], v[90:91], v[72:73]
	v_pk_fma_f32 v[16:17], v[28:29], v[96:97], v[12:13] op_sel:[1,0,0] op_sel_hi:[1,1,1]
	v_add_f32_e32 v74, v72, v73
	v_pk_fma_f32 v[18:19], v[28:29], v[98:99], v[14:15] op_sel:[1,0,0] op_sel_hi:[1,1,1]
	v_pk_mul_f32 v[198:199], v[12:13], v[136:137]
	v_add_f32_dpp v74, v74, v74 quad_perm:[1,0,3,2] row_mask:0xf bank_mask:0xf bound_ctrl:1
	v_pk_fma_f32 v[198:199], v[14:15], v[138:139], v[198:199]
	v_add_f32_e32 v172, v198, v199
	v_add_f32_dpp v74, v74, v74 quad_perm:[2,3,0,1] row_mask:0xf bank_mask:0xf bound_ctrl:1
	v_add_f32_dpp v180, v164, v164 row_mirror row_mask:0xf bank_mask:0x3
	s_nop 1
	v_add_f32_dpp v180, v172, v172 row_mirror row_mask:0xf bank_mask:0xc
	v_add_f32_dpp v74, v74, v74 row_half_mirror row_mask:0xf bank_mask:0xf bound_ctrl:1
	s_nop 1
	v_add_f32_dpp v74, v74, v74 row_mirror row_mask:0xf bank_mask:0xf bound_ctrl:1
	v_pk_fma_f32 v[12:13], v[92:93], v[74:75], v[16:17] op_sel_hi:[1,0,1] neg_lo:[0,1,0] neg_hi:[0,1,0]
	v_pk_fma_f32 v[14:15], v[94:95], v[74:75], v[18:19] op_sel_hi:[1,0,1] neg_lo:[0,1,0] neg_hi:[0,1,0]
	s_waitcnt lgkmcnt(0)
	v_pk_mul_f32 v[72:73], v[12:13], v[100:101]
	v_pk_fma_f32 v[72:73], v[14:15], v[102:103], v[72:73]
	v_pk_fma_f32 v[16:17], v[30:31], v[108:109], v[12:13] op_sel_hi:[0,1,1]
	v_add_f32_e32 v74, v72, v73
	v_pk_fma_f32 v[18:19], v[30:31], v[110:111], v[14:15] op_sel_hi:[0,1,1]
	v_pk_mul_f32 v[198:199], v[12:13], v[140:141]
	v_add_f32_dpp v74, v74, v74 quad_perm:[1,0,3,2] row_mask:0xf bank_mask:0xf bound_ctrl:1
	v_pk_fma_f32 v[198:199], v[14:15], v[142:143], v[198:199]
	v_add_f32_e32 v173, v198, v199
	v_add_f32_dpp v74, v74, v74 quad_perm:[2,3,0,1] row_mask:0xf bank_mask:0xf bound_ctrl:1
	v_add_f32_dpp v184, v176, v176 row_half_mirror row_mask:0xf bank_mask:0x5
	s_nop 1
	v_add_f32_dpp v184, v180, v180 row_half_mirror row_mask:0xf bank_mask:0xa
	v_add_f32_dpp v74, v74, v74 row_half_mirror row_mask:0xf bank_mask:0xf bound_ctrl:1
	s_nop 1
	v_add_f32_dpp v74, v74, v74 row_mirror row_mask:0xf bank_mask:0xf bound_ctrl:1
	v_pk_fma_f32 v[12:13], v[104:105], v[74:75], v[16:17] op_sel_hi:[1,0,1] neg_lo:[0,1,0] neg_hi:[0,1,0]
	v_pk_fma_f32 v[14:15], v[106:107], v[74:75], v[18:19] op_sel_hi:[1,0,1] neg_lo:[0,1,0] neg_hi:[0,1,0]
	v_pk_mul_f32 v[72:73], v[12:13], v[112:113]
	v_pk_fma_f32 v[72:73], v[14:15], v[114:115], v[72:73]
	v_pk_fma_f32 v[16:17], v[30:31], v[120:121], v[12:13] op_sel:[1,0,0] op_sel_hi:[1,1,1]
	v_add_f32_e32 v74, v72, v73
	v_pk_fma_f32 v[18:19], v[30:31], v[122:123], v[14:15] op_sel:[1,0,0] op_sel_hi:[1,1,1]
	v_pk_mul_f32 v[198:199], v[12:13], v[124:125]
	v_add_f32_dpp v74, v74, v74 quad_perm:[1,0,3,2] row_mask:0xf bank_mask:0xf bound_ctrl:1
	v_pk_fma_f32 v[198:199], v[14:15], v[126:127], v[198:199]
	v_add_f32_e32 v174, v198, v199
	v_add_f32_dpp v74, v74, v74 quad_perm:[2,3,0,1] row_mask:0xf bank_mask:0xf bound_ctrl:1
	v_add_f32_dpp v181, v165, v165 row_mirror row_mask:0xf bank_mask:0x3
	s_nop 0
	v_add_f32_dpp v74, v74, v74 row_half_mirror row_mask:0xf bank_mask:0xf bound_ctrl:1
	v_add_f32_dpp v185, v177, v177 row_half_mirror row_mask:0xf bank_mask:0x5
	v_add_f32_dpp v181, v173, v173 row_mirror row_mask:0xf bank_mask:0xc
	v_add_f32_dpp v74, v74, v74 row_mirror row_mask:0xf bank_mask:0xf bound_ctrl:1
	v_pk_fma_f32 v[12:13], v[116:117], v[74:75], v[16:17] op_sel_hi:[1,0,1] neg_lo:[0,1,0] neg_hi:[0,1,0]
	v_pk_fma_f32 v[14:15], v[118:119], v[74:75], v[18:19] op_sel_hi:[1,0,1] neg_lo:[0,1,0] neg_hi:[0,1,0]
	ds_read_b128 v[20:23], v4
	v_pk_mul_f32 v[198:199], v[12:13], v[128:129]
	v_pk_fma_f32 v[198:199], v[14:15], v[130:131], v[198:199]
	v_add_f32_e32 v175, v198, v199
	v_add_f32_dpp v185, v181, v181 row_half_mirror row_mask:0xf bank_mask:0xa
	v_add_f32_dpp v182, v166, v166 row_mirror row_mask:0xf bank_mask:0x3
	s_nop 1
	v_add_f32_dpp v182, v174, v174 row_mirror row_mask:0xf bank_mask:0xc
	v_add_f32_dpp v186, v178, v178 row_half_mirror row_mask:0xf bank_mask:0x5
	s_nop 1
	v_add_f32_dpp v186, v182, v182 row_half_mirror row_mask:0xf bank_mask:0xa
	v_cndmask_b32_e64 v190, v184, v186, s[98:99]
	v_cndmask_b32_e64 v191, v186, v184, s[98:99]
	s_nop 1
	v_add_f32_dpp v188, v191, v190 quad_perm:[2,3,0,1] row_mask:0xf bank_mask:0xf
	v_add_f32_dpp v183, v167, v167 row_mirror row_mask:0xf bank_mask:0x3
	s_nop 1
	v_add_f32_dpp v183, v175, v175 row_mirror row_mask:0xf bank_mask:0xc
	v_add_f32_dpp v187, v179, v179 row_half_mirror row_mask:0xf bank_mask:0x5
	s_waitcnt lgkmcnt(0)
	v_pk_mul_f32 v[12:13], v[12:13], v[20:21]
	v_add_f32_dpp v187, v183, v183 row_half_mirror row_mask:0xf bank_mask:0xa
	v_pk_mul_f32 v[14:15], v[14:15], v[22:23]
	v_cndmask_b32_e64 v190, v185, v187, s[98:99]
	v_cndmask_b32_e64 v191, v187, v185, s[98:99]
	s_nop 1
	v_add_f32_dpp v189, v191, v190 quad_perm:[2,3,0,1] row_mask:0xf bank_mask:0xf
	v_cndmask_b32_e64 v190, v188, v189, s[100:101]
	v_cndmask_b32_e64 v191, v189, v188, s[100:101]
	v_add_u32_e32 v196, 16, v5
	v_lshlrev_b32_e32 v194, 11, v196
	v_add_f32_dpp v192, v191, v190 quad_perm:[1,0,3,2] row_mask:0xf bank_mask:0xf
	v_mov_b32_e32 v195, 0
	v_cvt_pk_bf16_f32 v193, v192, v192
	v_lshl_add_u64 v[194:195], v[6:7], 0, v[194:195]
	global_store_short v[194:195], v193, off offset:1024
	v_add_u32_e32 v5, 32, v5
	s_bitcmp1_b32 s22, 0
	s_cselect_b32 s4, s39, s38
	v_add_u32_e32 v2, s4, v2
	v_add_u32_e32 v3, s4, v3
	v_add_u32_e32 v4, s4, v4
	s_add_i32 s22, s22, 1
	s_cmpk_lt_i32 s22, 128
	s_cbranch_scc1 .Lrw3_cloop
	global_store_dwordx4 v[8:9], v[12:15], off
	s_branch .LBB0_738
